# scan producer: cross-row prefix ds_bpermute steps issued early so their LDS latency overlaps the operand-load issue
# baseline (speedup 1.0000x reference)
.LBB0_299:
	ds_bpermute_b32 v242, v218, v134
	ds_bpermute_b32 v243, v218, v137
	s_add_i32 s25, s24, 2
	s_min_i32 s0, s25, s20
	s_lshl_b32 s0, s0, 5
	v_add_u32_e32 v20, s0, v56
	v_ashrrev_i32_e32 v21, 31, v20
	v_lshlrev_b64 v[20:21], 11, v[20:21]
	v_lshl_add_u64 v[20:21], v[20:21], 0, v[58:59]
	v_lshl_add_u64 v[22:23], v[20:21], 2, s[74:75]
	v_lshlrev_b64 v[20:21], 1, v[20:21]
	v_add_co_u32_e32 v26, vcc, s69, v22
	v_lshl_add_u64 v[24:25], s[64:65], 0, v[20:21]
	s_nop 0
	v_addc_co_u32_e32 v27, vcc, 0, v23, vcc
	v_lshlrev_b32_e32 v244, 16, v224
	v_and_b32_e32 v245, 0xffff0000, v224
	v_lshl_add_u64 v[20:21], s[72:73], 0, v[20:21]
	global_load_dwordx2 v[106:107], v[22:23], off
	global_load_dword v224, v[24:25], off
	global_load_dword v233, v[20:21], off
	global_load_dwordx2 v[102:103], v[26:27], off
	v_add_co_u32_e32 v26, vcc, s69, v24
	v_lshlrev_b32_e32 v246, 16, v227
	s_nop 0
	v_addc_co_u32_e32 v27, vcc, 0, v25, vcc
	v_add_co_u32_e32 v28, vcc, s69, v20
	v_and_b32_e32 v247, 0xffff0000, v227
	s_nop 0
	v_addc_co_u32_e32 v29, vcc, 0, v21, vcc
	v_add_co_u32_e32 v30, vcc, s66, v22
	v_lshlrev_b32_e32 v248, 16, v226
	s_nop 0
	v_addc_co_u32_e32 v31, vcc, 0, v23, vcc
	v_add_co_u32_e32 v32, vcc, s66, v24
	v_and_b32_e32 v249, 0xffff0000, v226
	s_nop 0
	v_addc_co_u32_e32 v33, vcc, 0, v25, vcc
	v_add_co_u32_e32 v34, vcc, s66, v20
	v_lshlrev_b32_e32 v172, 16, v222
	s_nop 0
	v_addc_co_u32_e32 v35, vcc, 0, v21, vcc
	v_and_b32_e32 v173, 0xffff0000, v222
	v_lshlrev_b32_e32 v170, 16, v223
	v_and_b32_e32 v171, 0xffff0000, v223
	global_load_dword v227, v[26:27], off offset:-4096
	global_load_dword v235, v[28:29], off offset:-4096
	global_load_dword v234, v[28:29], off
	global_load_dword v222, v[32:33], off offset:-4096
	global_load_dword v232, v[34:35], off offset:-4096
	global_load_dword v231, v[34:35], off
	global_load_dword v223, v[32:33], off
	global_load_dword v226, v[26:27], off
	s_waitcnt lgkmcnt(1)
	v_add_f32_e32 v162, v134, v242
	s_waitcnt lgkmcnt(0)
	v_add_f32_e32 v163, v137, v243
	v_cndmask_b32_e64 v162, v162, v134, s[40:41]
	v_cndmask_b32_e64 v163, v163, v137, s[40:41]
	s_nop 0
	ds_bpermute_b32 v242, v219, v162
	ds_bpermute_b32 v243, v219, v163
	v_add_co_u32_e32 v26, vcc, s63, v22
	v_lshlrev_b32_e32 v168, 16, v221
	s_nop 0
	v_addc_co_u32_e32 v27, vcc, 0, v23, vcc
	v_add_co_u32_e32 v28, vcc, s47, v22
	v_and_b32_e32 v169, 0xffff0000, v221
	s_nop 0
	v_addc_co_u32_e32 v29, vcc, 0, v23, vcc
	v_add_co_u32_e32 v32, vcc, s3, v22
	v_lshlrev_b32_e32 v166, 16, v228
	s_nop 0
	v_addc_co_u32_e32 v33, vcc, 0, v23, vcc
	global_load_dwordx2 v[118:119], v[30:31], off
	global_load_dwordx2 v[114:115], v[26:27], off
	global_load_dwordx2 v[100:101], v[28:29], off
	global_load_dwordx2 v[90:91], v[32:33], off
	v_add_co_u32_e32 v26, vcc, s63, v24
	v_and_b32_e32 v167, 0xffff0000, v228
	s_nop 0
	v_addc_co_u32_e32 v27, vcc, 0, v25, vcc
	v_add_co_u32_e32 v28, vcc, s63, v20
	s_ashr_i32 s1, s0, 31
	s_nop 0
	v_addc_co_u32_e32 v29, vcc, 0, v21, vcc
	v_add_co_u32_e32 v30, vcc, s67, v22
	global_load_dword v221, v[26:27], off offset:-4096
	global_load_dword v229, v[28:29], off offset:-4096
	global_load_dword v236, v[28:29], off
	global_load_dword v228, v[26:27], off
	v_addc_co_u32_e32 v31, vcc, 0, v23, vcc
	v_add_co_u32_e32 v22, vcc, s28, v22
	s_nop 0
	s_nop 0
	v_addc_co_u32_e32 v23, vcc, 0, v23, vcc
	v_add_co_u32_e32 v24, vcc, s33, v24
	v_lshlrev_b32_e32 v158, 16, v230
	s_nop 0
	v_addc_co_u32_e32 v25, vcc, 0, v25, vcc
	v_add_co_u32_e32 v20, vcc, s33, v20
	v_and_b32_e32 v159, 0xffff0000, v230
	s_nop 0
	v_addc_co_u32_e32 v21, vcc, 0, v21, vcc
	global_load_dwordx2 v[108:109], v[30:31], off
	global_load_dwordx2 v[128:129], v[22:23], off
	global_load_dword v230, v[24:25], off
	global_load_dword v237, v[20:21], off
	s_nop 0
	s_waitcnt lgkmcnt(1)
	v_add_f32_e32 v242, v162, v242
	s_waitcnt lgkmcnt(0)
	v_add_f32_e32 v243, v163, v243
	v_cndmask_b32_e64 v162, v162, v242, s[42:43]
	v_cndmask_b32_e64 v243, v163, v243, s[42:43]
	v_sub_f32_e32 v250, v162, v134
	v_sub_f32_e32 v211, v243, v137
	v_add_f32_e32 v207, v136, v250
	v_add_f32_e32 v139, v139, v211
	ds_bpermute_b32 v242, v220, v162
	v_exp_f32_e32 v162, v207
	v_exp_f32_e32 v163, v139
	v_exp_f32_e64 v207, -v207
	v_exp_f32_e64 v139, -v139
	v_add_f32_e32 v147, v147, v211
	v_pk_mul_f32 v[162:163], v[162:163], v[244:245]
	v_mul_f32_e32 v131, v131, v207
	v_add_f32_e32 v207, v138, v250
	v_cvt_pk_bf16_f32 v162, v162, v163
	v_mul_f32_e32 v163, v241, v139
	v_exp_f32_e32 v138, v207
	v_exp_f32_e32 v139, v147
	v_cvt_pk_bf16_f32 v163, v131, v163
	v_exp_f32_e64 v131, -v207
	v_exp_f32_e64 v147, -v147
	v_pk_mul_f32 v[138:139], v[138:139], v[246:247]
	v_add_f32_e32 v146, v146, v250
	v_cvt_pk_bf16_f32 v138, v138, v139
	v_mul_f32_e32 v131, v239, v131
	v_mul_f32_e32 v139, v240, v147
	v_add_f32_e32 v147, v149, v211
	v_cvt_pk_bf16_f32 v207, v131, v139
	ds_write2_b32 v49, v162, v138 offset1:66
	v_exp_f32_e32 v138, v146
	v_exp_f32_e32 v139, v147
	v_exp_f32_e64 v146, -v146
	v_exp_f32_e64 v147, -v147
	v_add_u32_e32 v131, 0x2000, v49
	v_pk_mul_f32 v[138:139], v[138:139], v[248:249]
	v_add_f32_e32 v148, v148, v250
	v_add_f32_e32 v143, v143, v211
	ds_write2_b32 v131, v163, v207 offset0:64 offset1:130
	v_cvt_pk_bf16_f32 v131, v138, v139
	v_pk_mul_f32 v[138:139], v[156:157], v[146:147]
	v_exp_f32_e32 v146, v148
	v_exp_f32_e32 v147, v143
	v_exp_f32_e64 v148, -v148
	v_exp_f32_e64 v149, -v143
	v_cvt_pk_bf16_f32 v156, v138, v139
	v_pk_mul_f32 v[138:139], v[146:147], v[172:173]
	v_add_f32_e32 v142, v142, v250
	v_cvt_pk_bf16_f32 v143, v138, v139
	v_pk_mul_f32 v[138:139], v[154:155], v[148:149]
	ds_write2_b32 v49, v131, v143 offset0:132 offset1:198
	v_add_f32_e32 v143, v145, v211
	v_cvt_pk_bf16_f32 v146, v138, v139
	v_exp_f32_e32 v138, v142
	v_exp_f32_e32 v139, v143
	v_exp_f32_e64 v142, -v142
	v_exp_f32_e64 v143, -v143
	v_add_u32_e32 v131, 0x2200, v49
	v_pk_mul_f32 v[138:139], v[138:139], v[170:171]
	v_add_f32_e32 v144, v144, v250
	v_add_f32_e32 v141, v141, v211
	ds_write2_b32 v131, v156, v146 offset0:68 offset1:134
	v_cvt_pk_bf16_f32 v131, v138, v139
	v_pk_mul_f32 v[138:139], v[152:153], v[142:143]
	v_exp_f32_e32 v142, v144
	v_exp_f32_e32 v143, v141
	v_exp_f32_e64 v144, -v144
	v_exp_f32_e64 v145, -v141
	v_cvt_pk_bf16_f32 v147, v138, v139
	v_pk_mul_f32 v[138:139], v[142:143], v[168:169]
	v_add_u32_e32 v143, 0x400, v49
	v_cvt_pk_bf16_f32 v141, v138, v139
	v_pk_mul_f32 v[138:139], v[150:151], v[144:145]
	v_add_f32_e32 v140, v140, v250
	v_add_f32_e32 v135, v135, v211
	v_cvt_pk_bf16_f32 v142, v138, v139
	ds_write2_b32 v143, v131, v141 offset0:8 offset1:74
	v_exp_f32_e32 v138, v140
	v_exp_f32_e32 v139, v135
	v_exp_f32_e64 v140, -v140
	v_exp_f32_e64 v141, -v135
	v_add_u32_e32 v131, 0x2400, v49
	ds_write2_b32 v131, v147, v142 offset0:72 offset1:138
	v_mov_b32_e32 v131, v133
	v_pk_mul_f32 v[138:139], v[138:139], v[166:167]
	v_pk_mul_f32 v[130:131], v[130:131], v[140:141]
	v_add_f32_e32 v133, v134, v250
	v_add_f32_e32 v137, v137, v211
	v_cvt_pk_bf16_f32 v138, v138, v139
	v_exp_f32_e32 v134, v133
	v_exp_f32_e32 v135, v137
	v_cvt_pk_bf16_f32 v139, v130, v131
	v_exp_f32_e64 v130, -v133
	v_exp_f32_e64 v131, -v137
	ds_bpermute_b32 v136, v220, v243
	v_mov_b32_e32 v133, v238
	v_pk_mul_f32 v[134:135], v[134:135], v[158:159]
	v_pk_mul_f32 v[130:131], v[132:133], v[130:131]
	v_cvt_pk_bf16_f32 v134, v134, v135
	v_cvt_pk_bf16_f32 v135, v130, v131
	v_add_u32_e32 v130, 0x2600, v49
	ds_write2_b32 v143, v138, v134 offset0:140 offset1:206
	ds_write2_b32 v130, v139, v135 offset0:76 offset1:142
	v_perm_b32 v130, v207, v163, s71
	v_perm_b32 v131, v146, v156, s71
	v_perm_b32 v132, v142, v147, s71
	v_perm_b32 v133, v135, v139, s71
	v_add_u32_e32 v134, v185, v179
	ds_write_b128 v134, v[130:133] offset:16896
	v_perm_b32 v130, v207, v163, s62
	v_perm_b32 v131, v146, v156, s62
	v_perm_b32 v132, v142, v147, s62
	v_perm_b32 v133, v135, v139, s62
	ds_write_b128 v134, v[130:133] offset:16976
	s_and_saveexec_b64 s[0:1], s[40:41]
	s_cbranch_execz .LBB0_301
	s_waitcnt lgkmcnt(11)
	v_exp_f32_e32 v130, v242
	s_waitcnt lgkmcnt(4)
	v_exp_f32_e32 v131, v136
	ds_write_b64 v187, v[130:131] offset:27136

.LBB0_309:
	ds_bpermute_b32 v242, v218, v145
	ds_bpermute_b32 v243, v218, v167
	s_add_i32 s0, s24, 3
	s_min_i32 s0, s0, s20
	s_lshl_b32 s0, s0, 5
	v_add_u32_e32 v4, s0, v56
	v_ashrrev_i32_e32 v5, 31, v4
	v_lshlrev_b64 v[4:5], 11, v[4:5]
	v_lshl_add_u64 v[4:5], v[4:5], 0, v[58:59]
	v_lshl_add_u64 v[6:7], v[4:5], 2, s[74:75]
	v_lshlrev_b64 v[4:5], 1, v[4:5]
	v_add_co_u32_e32 v10, vcc, s69, v6
	v_lshl_add_u64 v[8:9], s[64:65], 0, v[4:5]
	s_nop 0
	v_addc_co_u32_e32 v11, vcc, 0, v7, vcc
	v_lshlrev_b32_e32 v162, 16, v193
	v_and_b32_e32 v163, 0xffff0000, v193
	v_lshl_add_u64 v[4:5], s[72:73], 0, v[4:5]
	global_load_dwordx2 v[68:69], v[6:7], off
	global_load_dword v193, v[8:9], off
	global_load_dword v201, v[4:5], off
	global_load_dwordx2 v[104:105], v[10:11], off
	v_add_co_u32_e32 v10, vcc, s69, v8
	v_lshlrev_b32_e32 v244, 16, v194
	s_nop 0
	v_addc_co_u32_e32 v11, vcc, 0, v9, vcc
	v_add_co_u32_e32 v12, vcc, s69, v4
	v_and_b32_e32 v245, 0xffff0000, v194
	s_nop 0
	v_addc_co_u32_e32 v13, vcc, 0, v5, vcc
	v_add_co_u32_e32 v14, vcc, s66, v6
	v_lshlrev_b32_e32 v246, 16, v195
	s_nop 0
	v_addc_co_u32_e32 v15, vcc, 0, v7, vcc
	v_add_co_u32_e32 v16, vcc, s66, v8
	v_and_b32_e32 v247, 0xffff0000, v195
	s_nop 0
	v_addc_co_u32_e32 v17, vcc, 0, v9, vcc
	v_add_co_u32_e32 v18, vcc, s66, v4
	v_lshlrev_b32_e32 v156, 16, v191
	s_nop 0
	v_addc_co_u32_e32 v19, vcc, 0, v5, vcc
	v_and_b32_e32 v157, 0xffff0000, v191
	v_lshlrev_b32_e32 v154, 16, v190
	v_and_b32_e32 v155, 0xffff0000, v190
	global_load_dword v194, v[10:11], off offset:-4096
	global_load_dword v215, v[12:13], off offset:-4096
	global_load_dword v202, v[12:13], off
	global_load_dword v191, v[16:17], off offset:-4096
	global_load_dword v200, v[18:19], off offset:-4096
	global_load_dword v197, v[18:19], off
	global_load_dword v190, v[16:17], off
	global_load_dword v195, v[10:11], off
	s_waitcnt lgkmcnt(1)
	v_add_f32_e32 v207, v145, v242
	s_waitcnt lgkmcnt(0)
	v_add_f32_e32 v211, v167, v243
	v_cndmask_b32_e64 v207, v207, v145, s[40:41]
	v_cndmask_b32_e64 v211, v211, v167, s[40:41]
	s_nop 0
	ds_bpermute_b32 v242, v219, v207
	ds_bpermute_b32 v243, v219, v211
	v_add_co_u32_e32 v10, vcc, s63, v6
	v_lshlrev_b32_e32 v152, 16, v192
	s_nop 0
	v_addc_co_u32_e32 v11, vcc, 0, v7, vcc
	v_add_co_u32_e32 v12, vcc, s47, v6
	v_and_b32_e32 v153, 0xffff0000, v192
	s_nop 0
	v_addc_co_u32_e32 v13, vcc, 0, v7, vcc
	v_add_co_u32_e32 v16, vcc, s3, v6
	v_lshlrev_b32_e32 v150, 16, v189
	s_nop 0
	v_addc_co_u32_e32 v17, vcc, 0, v7, vcc
	global_load_dwordx2 v[76:77], v[14:15], off
	global_load_dwordx2 v[72:73], v[10:11], off
	global_load_dwordx2 v[70:71], v[12:13], off
	global_load_dwordx2 v[62:63], v[16:17], off
	v_add_co_u32_e32 v10, vcc, s63, v8
	v_and_b32_e32 v151, 0xffff0000, v189
	s_nop 0
	v_addc_co_u32_e32 v11, vcc, 0, v9, vcc
	v_add_co_u32_e32 v12, vcc, s63, v4
	s_ashr_i32 s1, s0, 31
	s_nop 0
	v_addc_co_u32_e32 v13, vcc, 0, v5, vcc
	v_add_co_u32_e32 v14, vcc, s67, v6
	global_load_dword v192, v[10:11], off offset:-4096
	global_load_dword v198, v[12:13], off offset:-4096
	global_load_dword v196, v[12:13], off
	global_load_dword v189, v[10:11], off
	v_addc_co_u32_e32 v15, vcc, 0, v7, vcc
	v_add_co_u32_e32 v6, vcc, s28, v6
	s_nop 0
	s_nop 0
	v_addc_co_u32_e32 v7, vcc, 0, v7, vcc
	v_add_co_u32_e32 v8, vcc, s33, v8
	v_lshlrev_b32_e32 v148, 16, v199
	s_nop 0
	v_addc_co_u32_e32 v9, vcc, 0, v9, vcc
	v_add_co_u32_e32 v4, vcc, s33, v4
	v_and_b32_e32 v149, 0xffff0000, v199
	s_nop 0
	v_addc_co_u32_e32 v5, vcc, 0, v5, vcc
	global_load_dwordx2 v[66:67], v[14:15], off
	global_load_dwordx2 v[64:65], v[6:7], off
	global_load_dword v199, v[8:9], off
	global_load_dword v225, v[4:5], off
	s_nop 0
	s_waitcnt lgkmcnt(1)
	v_add_f32_e32 v242, v207, v242
	s_waitcnt lgkmcnt(0)
	v_add_f32_e32 v243, v211, v243
	v_cndmask_b32_e64 v207, v207, v242, s[42:43]
	v_cndmask_b32_e64 v211, v211, v243, s[42:43]
	ds_bpermute_b32 v242, v220, v207
	v_sub_f32_e32 v207, v207, v145
	v_sub_f32_e32 v243, v211, v167
	v_add_f32_e32 v144, v144, v207
	v_add_f32_e32 v250, v143, v243
	v_exp_f32_e32 v248, v144
	ds_bpermute_b32 v143, v220, v211
	v_exp_f32_e64 v144, -v144
	v_exp_f32_e64 v211, -v250
	v_exp_f32_e32 v249, v250
	v_mul_f32_e32 v141, v141, v144
	v_mul_f32_e32 v144, v169, v211
	v_pk_mul_f32 v[162:163], v[248:249], v[162:163]
	v_cvt_pk_bf16_f32 v144, v141, v144
	v_add_f32_e32 v141, v142, v207
	v_add_f32_e32 v142, v147, v243
	v_cvt_pk_bf16_f32 v250, v162, v163
	v_exp_f32_e32 v162, v141
	v_exp_f32_e32 v163, v142
	v_exp_f32_e64 v248, -v141
	v_exp_f32_e64 v249, -v142
	v_add_u32_e32 v169, v46, v184
	v_pk_mul_f32 v[162:163], v[162:163], v[244:245]
	v_mov_b32_e32 v141, v139
	v_cvt_pk_bf16_f32 v142, v162, v163
	v_add_u32_e32 v163, 0x6c00, v169
	v_pk_mul_f32 v[140:141], v[140:141], v[248:249]
	ds_write2_b32 v163, v250, v142 offset1:66
	v_add_f32_e32 v142, v146, v207
	v_add_f32_e32 v147, v241, v243
	v_cvt_pk_bf16_f32 v162, v140, v141
	v_exp_f32_e32 v140, v142
	v_exp_f32_e32 v141, v147
	v_exp_f32_e64 v146, -v142
	v_exp_f32_e64 v147, -v147
	v_add_u32_e32 v139, 0x8c00, v169
	ds_write2_b32 v139, v144, v162 offset0:64 offset1:130
	v_mov_b32_e32 v139, v166
	v_pk_mul_f32 v[140:141], v[140:141], v[246:247]
	v_pk_mul_f32 v[138:139], v[138:139], v[146:147]
	v_add_f32_e32 v146, v239, v207
	v_add_f32_e32 v147, v240, v243
	v_cvt_pk_bf16_f32 v142, v140, v141
	v_exp_f32_e32 v140, v146
	v_exp_f32_e32 v141, v147
	v_exp_f32_e64 v146, -v146
	v_exp_f32_e64 v147, -v147
	v_cvt_pk_bf16_f32 v166, v138, v139
	v_pk_mul_f32 v[138:139], v[140:141], v[156:157]
	v_mul_f32_e32 v135, v135, v146
	v_cvt_pk_bf16_f32 v138, v138, v139
	v_mul_f32_e32 v139, v159, v147
	v_add_f32_e32 v140, v173, v207
	v_add_f32_e32 v141, v238, v243
	v_cvt_pk_bf16_f32 v146, v135, v139
	ds_write2_b32 v163, v142, v138 offset0:132 offset1:198
	v_exp_f32_e32 v138, v140
	v_exp_f32_e32 v139, v141
	v_exp_f32_e64 v140, -v140
	v_exp_f32_e64 v141, -v141
	v_add_u32_e32 v135, 0x8e00, v169
	ds_write2_b32 v135, v166, v146 offset0:68 offset1:134
	v_mov_b32_e32 v135, v137
	v_pk_mul_f32 v[138:139], v[138:139], v[154:155]
	v_pk_mul_f32 v[134:135], v[134:135], v[140:141]
	v_add_f32_e32 v137, v171, v207
	v_add_f32_e32 v140, v172, v243
	v_cvt_pk_bf16_f32 v142, v138, v139
	v_exp_f32_e32 v138, v137
	v_exp_f32_e32 v139, v140
	v_cvt_pk_bf16_f32 v141, v134, v135
	v_exp_f32_e64 v134, -v137
	v_exp_f32_e64 v135, -v140
	v_mov_b32_e32 v137, v131
	v_pk_mul_f32 v[138:139], v[138:139], v[152:153]
	v_add_u32_e32 v131, 0x9000, v169
	v_pk_mul_f32 v[134:135], v[136:137], v[134:135]
	v_add_f32_e32 v136, v168, v207
	v_add_f32_e32 v137, v170, v243
	v_cvt_pk_bf16_f32 v138, v138, v139
	v_cvt_pk_bf16_f32 v139, v134, v135
	v_exp_f32_e32 v134, v136
	v_exp_f32_e32 v135, v137
	v_exp_f32_e64 v136, -v136
	v_exp_f32_e64 v137, -v137
	ds_write2_b32 v131, v141, v139 offset0:72 offset1:138
	v_mov_b32_e32 v131, v133
	v_add_u32_e32 v140, 0x7000, v169
	v_pk_mul_f32 v[134:135], v[134:135], v[150:151]
	v_pk_mul_f32 v[130:131], v[130:131], v[136:137]
	v_add_f32_e32 v133, v145, v207
	v_add_f32_e32 v136, v167, v243
	ds_write2_b32 v140, v142, v138 offset0:8 offset1:74
	v_cvt_pk_bf16_f32 v138, v134, v135
	v_exp_f32_e32 v134, v133
	v_exp_f32_e32 v135, v136
	v_cvt_pk_bf16_f32 v137, v130, v131
	v_exp_f32_e64 v130, -v133
	v_exp_f32_e64 v131, -v136
	v_mov_b32_e32 v133, v158
	v_pk_mul_f32 v[134:135], v[134:135], v[148:149]
	v_pk_mul_f32 v[130:131], v[132:133], v[130:131]
	v_cvt_pk_bf16_f32 v134, v134, v135
	v_cvt_pk_bf16_f32 v135, v130, v131
	v_add_u32_e32 v130, 0x9200, v169
	ds_write2_b32 v140, v138, v134 offset0:140 offset1:206
	ds_write2_b32 v130, v137, v135 offset0:76 offset1:142
	v_perm_b32 v130, v162, v144, s71
	v_perm_b32 v131, v146, v166, s71
	v_perm_b32 v132, v139, v141, s71
	v_perm_b32 v133, v135, v137, s71
	v_add_u32_e32 v134, v48, v179
	ds_write_b128 v134, v[130:133] offset:44544
	v_perm_b32 v130, v162, v144, s62
	v_perm_b32 v131, v146, v166, s62
	v_perm_b32 v132, v139, v141, s62
	v_perm_b32 v133, v135, v137, s62
	ds_write_b128 v134, v[130:133] offset:44624
	s_and_saveexec_b64 s[0:1], s[40:41]
	s_cbranch_execz .LBB0_290
	s_waitcnt lgkmcnt(11)
	v_exp_f32_e32 v130, v242
	s_waitcnt lgkmcnt(10)
	v_exp_f32_e32 v131, v143
	v_add_u32_e32 v132, v48, v186
	ds_write_b64 v132, v[130:131] offset:54784
	s_branch .LBB0_290
